# adds hand-written final RMSNorm (8 rows per wave in flight, DPP row sums)
# speedup vs baseline: 1.0741x; 1.0020x over previous
.LBB0_3476:
	s_or_b64 exec, exec, s[0:1]
	s_waitcnt lgkmcnt(0)
	s_barrier
	v_lshrrev_b32_e32 v0, 6, v194
	s_lshl_b32 s5, s64, 3
	v_readfirstlane_b32 s4, v0
	s_add_i32 s4, s4, s33
	s_cmp_lt_u32 s4, 0x4000
	s_cbranch_scc0 .Lfin_done_FIN
	v_and_b32_e32 v1, 63, v194
	v_mov_b32_e32 v2, 0
	global_load_dwordx2 v[4:5], v2, s[66:67] offset:248
	v_lshlrev_b32_e32 v3, 4, v1
	v_and_b32_e32 v6, 15, v1
	v_lshlrev_b32_e32 v6, 2, v6
	v_mov_b32_e32 v7, 0x358637bd
	s_add_u32 s8, s66, 0x3500000
	s_addc_u32 s9, s67, 0
	v_mov_b32_e32 v8, v3
	v_mov_b32_e32 v9, 0
	s_waitcnt vmcnt(0)
	v_lshl_add_u64 v[4:5], v[4:5], 0, v[8:9]
	global_load_dwordx4 v[12:15], v[4:5], off
	global_load_dwordx4 v[16:19], v[4:5], off offset:1024
	global_load_dwordx4 v[20:23], v[4:5], off offset:2048
	global_load_dwordx4 v[24:27], v[4:5], off offset:3072
.Lfin_loop_FIN:
	s_mov_b32 s6, s4
	v_lshl_add_u32 v28, s6, 12, v3
	v_lshl_add_u32 v36, s6, 6, v6
	global_load_dword v44, v36, s[8:9]
	global_load_dwordx4 v[52:55], v28, s[68:69]
	global_load_dwordx4 v[56:59], v28, s[68:69] offset:1024
	global_load_dwordx4 v[60:63], v28, s[68:69] offset:2048
	global_load_dwordx4 v[64:67], v28, s[68:69] offset:3072
	s_mul_i32 s6, s5, 1
	s_add_i32 s6, s6, s4
	s_cmp_lt_u32 s6, 0x4000
	s_cselect_b32 s6, s6, s4
	v_lshl_add_u32 v29, s6, 12, v3
	v_lshl_add_u32 v37, s6, 6, v6
	global_load_dword v45, v37, s[8:9]
	global_load_dwordx4 v[68:71], v29, s[68:69]
	global_load_dwordx4 v[72:75], v29, s[68:69] offset:1024
	global_load_dwordx4 v[76:79], v29, s[68:69] offset:2048
	global_load_dwordx4 v[80:83], v29, s[68:69] offset:3072
	s_mul_i32 s6, s5, 2
	s_add_i32 s6, s6, s4
	s_cmp_lt_u32 s6, 0x4000
	s_cselect_b32 s6, s6, s4
	v_lshl_add_u32 v30, s6, 12, v3
	v_lshl_add_u32 v38, s6, 6, v6
	global_load_dword v46, v38, s[8:9]
	global_load_dwordx4 v[84:87], v30, s[68:69]
	global_load_dwordx4 v[88:91], v30, s[68:69] offset:1024
	global_load_dwordx4 v[92:95], v30, s[68:69] offset:2048
	global_load_dwordx4 v[96:99], v30, s[68:69] offset:3072
	s_mul_i32 s6, s5, 3
	s_add_i32 s6, s6, s4
	s_cmp_lt_u32 s6, 0x4000
	s_cselect_b32 s6, s6, s4
	v_lshl_add_u32 v31, s6, 12, v3
	v_lshl_add_u32 v39, s6, 6, v6
	global_load_dword v47, v39, s[8:9]
	global_load_dwordx4 v[100:103], v31, s[68:69]
	global_load_dwordx4 v[104:107], v31, s[68:69] offset:1024
	global_load_dwordx4 v[108:111], v31, s[68:69] offset:2048
	global_load_dwordx4 v[112:115], v31, s[68:69] offset:3072
	s_mul_i32 s6, s5, 4
	s_add_i32 s6, s6, s4
	s_cmp_lt_u32 s6, 0x4000
	s_cselect_b32 s6, s6, s4
	v_lshl_add_u32 v32, s6, 12, v3
	v_lshl_add_u32 v40, s6, 6, v6
	global_load_dword v48, v40, s[8:9]
	global_load_dwordx4 v[116:119], v32, s[68:69]
	global_load_dwordx4 v[120:123], v32, s[68:69] offset:1024
	global_load_dwordx4 v[124:127], v32, s[68:69] offset:2048
	global_load_dwordx4 v[128:131], v32, s[68:69] offset:3072
	s_mul_i32 s6, s5, 5
	s_add_i32 s6, s6, s4
	s_cmp_lt_u32 s6, 0x4000
	s_cselect_b32 s6, s6, s4
	v_lshl_add_u32 v33, s6, 12, v3
	v_lshl_add_u32 v41, s6, 6, v6
	global_load_dword v49, v41, s[8:9]
	global_load_dwordx4 v[132:135], v33, s[68:69]
	global_load_dwordx4 v[136:139], v33, s[68:69] offset:1024
	global_load_dwordx4 v[140:143], v33, s[68:69] offset:2048
	global_load_dwordx4 v[144:147], v33, s[68:69] offset:3072
	s_mul_i32 s6, s5, 6
	s_add_i32 s6, s6, s4
	s_cmp_lt_u32 s6, 0x4000
	s_cselect_b32 s6, s6, s4
	v_lshl_add_u32 v34, s6, 12, v3
	v_lshl_add_u32 v42, s6, 6, v6
	global_load_dword v50, v42, s[8:9]
	global_load_dwordx4 v[148:151], v34, s[68:69]
	global_load_dwordx4 v[152:155], v34, s[68:69] offset:1024
	global_load_dwordx4 v[156:159], v34, s[68:69] offset:2048
	global_load_dwordx4 v[160:163], v34, s[68:69] offset:3072
	s_mul_i32 s6, s5, 7
	s_add_i32 s6, s6, s4
	s_cmp_lt_u32 s6, 0x4000
	s_cselect_b32 s6, s6, s4
	v_lshl_add_u32 v35, s6, 12, v3
	v_lshl_add_u32 v43, s6, 6, v6
	global_load_dword v51, v43, s[8:9]
	global_load_dwordx4 v[164:167], v35, s[68:69]
	global_load_dwordx4 v[168:171], v35, s[68:69] offset:1024
	global_load_dwordx4 v[172:175], v35, s[68:69] offset:2048
	global_load_dwordx4 v[176:179], v35, s[68:69] offset:3072
	s_waitcnt vmcnt(35)
	v_add_f32_dpp v44, v44, v44 quad_perm:[1,0,3,2] row_mask:0xf bank_mask:0xf
	s_nop 1
	v_add_f32_dpp v44, v44, v44 quad_perm:[2,3,0,1] row_mask:0xf bank_mask:0xf
	s_nop 1
	v_add_f32_dpp v44, v44, v44 row_half_mirror row_mask:0xf bank_mask:0xf
	s_nop 1
	v_add_f32_dpp v44, v44, v44 row_mirror row_mask:0xf bank_mask:0xf
	v_fmamk_f32 v44, v44, 0x3a800000, v7
	v_rsq_f32_e32 v44, v44
	s_nop 0
	v_mul_f32_e32 v52, v44, v52
	v_mul_f32_e32 v53, v44, v53
	v_mul_f32_e32 v54, v44, v54
	v_mul_f32_e32 v55, v44, v55
	v_mul_f32_e32 v56, v44, v56
	v_mul_f32_e32 v57, v44, v57
	v_mul_f32_e32 v58, v44, v58
	v_mul_f32_e32 v59, v44, v59
	v_mul_f32_e32 v60, v44, v60
	v_mul_f32_e32 v61, v44, v61
	v_mul_f32_e32 v62, v44, v62
	v_mul_f32_e32 v63, v44, v63
	v_mul_f32_e32 v64, v44, v64
	v_mul_f32_e32 v65, v44, v65
	v_mul_f32_e32 v66, v44, v66
	v_mul_f32_e32 v67, v44, v67
	v_mul_f32_e32 v52, v52, v12
	v_mul_f32_e32 v53, v53, v13
	v_mul_f32_e32 v54, v54, v14
	v_mul_f32_e32 v55, v55, v15
	v_mul_f32_e32 v56, v56, v16
	v_mul_f32_e32 v57, v57, v17
	v_mul_f32_e32 v58, v58, v18
	v_mul_f32_e32 v59, v59, v19
	v_mul_f32_e32 v60, v60, v20
	v_mul_f32_e32 v61, v61, v21
	v_mul_f32_e32 v62, v62, v22
	v_mul_f32_e32 v63, v63, v23
	v_mul_f32_e32 v64, v64, v24
	v_mul_f32_e32 v65, v65, v25
	v_mul_f32_e32 v66, v66, v26
	v_mul_f32_e32 v67, v67, v27
	global_store_dwordx4 v28, v[52:55], s[68:69]
	global_store_dwordx4 v28, v[56:59], s[68:69] offset:1024
	global_store_dwordx4 v28, v[60:63], s[68:69] offset:2048
	global_store_dwordx4 v28, v[64:67], s[68:69] offset:3072
	s_mul_i32 s6, s5, 1
	s_add_i32 s6, s6, s4
	s_cmp_lt_u32 s6, 0x4000
	s_cbranch_scc0 .Lfin_skip_FIN_1
	s_waitcnt vmcnt(34)
	v_add_f32_dpp v45, v45, v45 quad_perm:[1,0,3,2] row_mask:0xf bank_mask:0xf
	s_nop 1
	v_add_f32_dpp v45, v45, v45 quad_perm:[2,3,0,1] row_mask:0xf bank_mask:0xf
	s_nop 1
	v_add_f32_dpp v45, v45, v45 row_half_mirror row_mask:0xf bank_mask:0xf
	s_nop 1
	v_add_f32_dpp v45, v45, v45 row_mirror row_mask:0xf bank_mask:0xf
	v_fmamk_f32 v45, v45, 0x3a800000, v7
	v_rsq_f32_e32 v45, v45
	s_nop 0
	v_mul_f32_e32 v68, v45, v68
	v_mul_f32_e32 v69, v45, v69
	v_mul_f32_e32 v70, v45, v70
	v_mul_f32_e32 v71, v45, v71
	v_mul_f32_e32 v72, v45, v72
	v_mul_f32_e32 v73, v45, v73
	v_mul_f32_e32 v74, v45, v74
	v_mul_f32_e32 v75, v45, v75
	v_mul_f32_e32 v76, v45, v76
	v_mul_f32_e32 v77, v45, v77
	v_mul_f32_e32 v78, v45, v78
	v_mul_f32_e32 v79, v45, v79
	v_mul_f32_e32 v80, v45, v80
	v_mul_f32_e32 v81, v45, v81
	v_mul_f32_e32 v82, v45, v82
	v_mul_f32_e32 v83, v45, v83
	v_mul_f32_e32 v68, v68, v12
	v_mul_f32_e32 v69, v69, v13
	v_mul_f32_e32 v70, v70, v14
	v_mul_f32_e32 v71, v71, v15
	v_mul_f32_e32 v72, v72, v16
	v_mul_f32_e32 v73, v73, v17
	v_mul_f32_e32 v74, v74, v18
	v_mul_f32_e32 v75, v75, v19
	v_mul_f32_e32 v76, v76, v20
	v_mul_f32_e32 v77, v77, v21
	v_mul_f32_e32 v78, v78, v22
	v_mul_f32_e32 v79, v79, v23
	v_mul_f32_e32 v80, v80, v24
	v_mul_f32_e32 v81, v81, v25
	v_mul_f32_e32 v82, v82, v26
	v_mul_f32_e32 v83, v83, v27
	global_store_dwordx4 v29, v[68:71], s[68:69]
	global_store_dwordx4 v29, v[72:75], s[68:69] offset:1024
	global_store_dwordx4 v29, v[76:79], s[68:69] offset:2048
	global_store_dwordx4 v29, v[80:83], s[68:69] offset:3072
.Lfin_skip_FIN_1:
	s_mul_i32 s6, s5, 2
	s_add_i32 s6, s6, s4
	s_cmp_lt_u32 s6, 0x4000
	s_cbranch_scc0 .Lfin_skip_FIN_2
	s_waitcnt vmcnt(33)
	v_add_f32_dpp v46, v46, v46 quad_perm:[1,0,3,2] row_mask:0xf bank_mask:0xf
	s_nop 1
	v_add_f32_dpp v46, v46, v46 quad_perm:[2,3,0,1] row_mask:0xf bank_mask:0xf
	s_nop 1
	v_add_f32_dpp v46, v46, v46 row_half_mirror row_mask:0xf bank_mask:0xf
	s_nop 1
	v_add_f32_dpp v46, v46, v46 row_mirror row_mask:0xf bank_mask:0xf
	v_fmamk_f32 v46, v46, 0x3a800000, v7
	v_rsq_f32_e32 v46, v46
	s_nop 0
	v_mul_f32_e32 v84, v46, v84
	v_mul_f32_e32 v85, v46, v85
	v_mul_f32_e32 v86, v46, v86
	v_mul_f32_e32 v87, v46, v87
	v_mul_f32_e32 v88, v46, v88
	v_mul_f32_e32 v89, v46, v89
	v_mul_f32_e32 v90, v46, v90
	v_mul_f32_e32 v91, v46, v91
	v_mul_f32_e32 v92, v46, v92
	v_mul_f32_e32 v93, v46, v93
	v_mul_f32_e32 v94, v46, v94
	v_mul_f32_e32 v95, v46, v95
	v_mul_f32_e32 v96, v46, v96
	v_mul_f32_e32 v97, v46, v97
	v_mul_f32_e32 v98, v46, v98
	v_mul_f32_e32 v99, v46, v99
	v_mul_f32_e32 v84, v84, v12
	v_mul_f32_e32 v85, v85, v13
	v_mul_f32_e32 v86, v86, v14
	v_mul_f32_e32 v87, v87, v15
	v_mul_f32_e32 v88, v88, v16
	v_mul_f32_e32 v89, v89, v17
	v_mul_f32_e32 v90, v90, v18
	v_mul_f32_e32 v91, v91, v19
	v_mul_f32_e32 v92, v92, v20
	v_mul_f32_e32 v93, v93, v21
	v_mul_f32_e32 v94, v94, v22
	v_mul_f32_e32 v95, v95, v23
	v_mul_f32_e32 v96, v96, v24
	v_mul_f32_e32 v97, v97, v25
	v_mul_f32_e32 v98, v98, v26
	v_mul_f32_e32 v99, v99, v27
	global_store_dwordx4 v30, v[84:87], s[68:69]
	global_store_dwordx4 v30, v[88:91], s[68:69] offset:1024
	global_store_dwordx4 v30, v[92:95], s[68:69] offset:2048
	global_store_dwordx4 v30, v[96:99], s[68:69] offset:3072
.Lfin_skip_FIN_2:
	s_mul_i32 s6, s5, 3
	s_add_i32 s6, s6, s4
	s_cmp_lt_u32 s6, 0x4000
	s_cbranch_scc0 .Lfin_skip_FIN_3
	s_waitcnt vmcnt(32)
	v_add_f32_dpp v47, v47, v47 quad_perm:[1,0,3,2] row_mask:0xf bank_mask:0xf
	s_nop 1
	v_add_f32_dpp v47, v47, v47 quad_perm:[2,3,0,1] row_mask:0xf bank_mask:0xf
	s_nop 1
	v_add_f32_dpp v47, v47, v47 row_half_mirror row_mask:0xf bank_mask:0xf
	s_nop 1
	v_add_f32_dpp v47, v47, v47 row_mirror row_mask:0xf bank_mask:0xf
	v_fmamk_f32 v47, v47, 0x3a800000, v7
	v_rsq_f32_e32 v47, v47
	s_nop 0
	v_mul_f32_e32 v100, v47, v100
	v_mul_f32_e32 v101, v47, v101
	v_mul_f32_e32 v102, v47, v102
	v_mul_f32_e32 v103, v47, v103
	v_mul_f32_e32 v104, v47, v104
	v_mul_f32_e32 v105, v47, v105
	v_mul_f32_e32 v106, v47, v106
	v_mul_f32_e32 v107, v47, v107
	v_mul_f32_e32 v108, v47, v108
	v_mul_f32_e32 v109, v47, v109
	v_mul_f32_e32 v110, v47, v110
	v_mul_f32_e32 v111, v47, v111
	v_mul_f32_e32 v112, v47, v112
	v_mul_f32_e32 v113, v47, v113
	v_mul_f32_e32 v114, v47, v114
	v_mul_f32_e32 v115, v47, v115
	v_mul_f32_e32 v100, v100, v12
	v_mul_f32_e32 v101, v101, v13
	v_mul_f32_e32 v102, v102, v14
	v_mul_f32_e32 v103, v103, v15
	v_mul_f32_e32 v104, v104, v16
	v_mul_f32_e32 v105, v105, v17
	v_mul_f32_e32 v106, v106, v18
	v_mul_f32_e32 v107, v107, v19
	v_mul_f32_e32 v108, v108, v20
	v_mul_f32_e32 v109, v109, v21
	v_mul_f32_e32 v110, v110, v22
	v_mul_f32_e32 v111, v111, v23
	v_mul_f32_e32 v112, v112, v24
	v_mul_f32_e32 v113, v113, v25
	v_mul_f32_e32 v114, v114, v26
	v_mul_f32_e32 v115, v115, v27
	global_store_dwordx4 v31, v[100:103], s[68:69]
	global_store_dwordx4 v31, v[104:107], s[68:69] offset:1024
	global_store_dwordx4 v31, v[108:111], s[68:69] offset:2048
	global_store_dwordx4 v31, v[112:115], s[68:69] offset:3072
.Lfin_skip_FIN_3:
	s_mul_i32 s6, s5, 4
	s_add_i32 s6, s6, s4
	s_cmp_lt_u32 s6, 0x4000
	s_cbranch_scc0 .Lfin_skip_FIN_4
	s_waitcnt vmcnt(31)
	v_add_f32_dpp v48, v48, v48 quad_perm:[1,0,3,2] row_mask:0xf bank_mask:0xf
	s_nop 1
	v_add_f32_dpp v48, v48, v48 quad_perm:[2,3,0,1] row_mask:0xf bank_mask:0xf
	s_nop 1
	v_add_f32_dpp v48, v48, v48 row_half_mirror row_mask:0xf bank_mask:0xf
	s_nop 1
	v_add_f32_dpp v48, v48, v48 row_mirror row_mask:0xf bank_mask:0xf
	v_fmamk_f32 v48, v48, 0x3a800000, v7
	v_rsq_f32_e32 v48, v48
	s_nop 0
	v_mul_f32_e32 v116, v48, v116
	v_mul_f32_e32 v117, v48, v117
	v_mul_f32_e32 v118, v48, v118
	v_mul_f32_e32 v119, v48, v119
	v_mul_f32_e32 v120, v48, v120
	v_mul_f32_e32 v121, v48, v121
	v_mul_f32_e32 v122, v48, v122
	v_mul_f32_e32 v123, v48, v123
	v_mul_f32_e32 v124, v48, v124
	v_mul_f32_e32 v125, v48, v125
	v_mul_f32_e32 v126, v48, v126
	v_mul_f32_e32 v127, v48, v127
	v_mul_f32_e32 v128, v48, v128
	v_mul_f32_e32 v129, v48, v129
	v_mul_f32_e32 v130, v48, v130
	v_mul_f32_e32 v131, v48, v131
	v_mul_f32_e32 v116, v116, v12
	v_mul_f32_e32 v117, v117, v13
	v_mul_f32_e32 v118, v118, v14
	v_mul_f32_e32 v119, v119, v15
	v_mul_f32_e32 v120, v120, v16
	v_mul_f32_e32 v121, v121, v17
	v_mul_f32_e32 v122, v122, v18
	v_mul_f32_e32 v123, v123, v19
	v_mul_f32_e32 v124, v124, v20
	v_mul_f32_e32 v125, v125, v21
	v_mul_f32_e32 v126, v126, v22
	v_mul_f32_e32 v127, v127, v23
	v_mul_f32_e32 v128, v128, v24
	v_mul_f32_e32 v129, v129, v25
	v_mul_f32_e32 v130, v130, v26
	v_mul_f32_e32 v131, v131, v27
	global_store_dwordx4 v32, v[116:119], s[68:69]
	global_store_dwordx4 v32, v[120:123], s[68:69] offset:1024
	global_store_dwordx4 v32, v[124:127], s[68:69] offset:2048
	global_store_dwordx4 v32, v[128:131], s[68:69] offset:3072
.Lfin_skip_FIN_4:
	s_mul_i32 s6, s5, 5
	s_add_i32 s6, s6, s4
	s_cmp_lt_u32 s6, 0x4000
	s_cbranch_scc0 .Lfin_skip_FIN_5
	s_waitcnt vmcnt(30)
	v_add_f32_dpp v49, v49, v49 quad_perm:[1,0,3,2] row_mask:0xf bank_mask:0xf
	s_nop 1
	v_add_f32_dpp v49, v49, v49 quad_perm:[2,3,0,1] row_mask:0xf bank_mask:0xf
	s_nop 1
	v_add_f32_dpp v49, v49, v49 row_half_mirror row_mask:0xf bank_mask:0xf
	s_nop 1
	v_add_f32_dpp v49, v49, v49 row_mirror row_mask:0xf bank_mask:0xf
	v_fmamk_f32 v49, v49, 0x3a800000, v7
	v_rsq_f32_e32 v49, v49
	s_nop 0
	v_mul_f32_e32 v132, v49, v132
	v_mul_f32_e32 v133, v49, v133
	v_mul_f32_e32 v134, v49, v134
	v_mul_f32_e32 v135, v49, v135
	v_mul_f32_e32 v136, v49, v136
	v_mul_f32_e32 v137, v49, v137
	v_mul_f32_e32 v138, v49, v138
	v_mul_f32_e32 v139, v49, v139
	v_mul_f32_e32 v140, v49, v140
	v_mul_f32_e32 v141, v49, v141
	v_mul_f32_e32 v142, v49, v142
	v_mul_f32_e32 v143, v49, v143
	v_mul_f32_e32 v144, v49, v144
	v_mul_f32_e32 v145, v49, v145
	v_mul_f32_e32 v146, v49, v146
	v_mul_f32_e32 v147, v49, v147
	v_mul_f32_e32 v132, v132, v12
	v_mul_f32_e32 v133, v133, v13
	v_mul_f32_e32 v134, v134, v14
	v_mul_f32_e32 v135, v135, v15
	v_mul_f32_e32 v136, v136, v16
	v_mul_f32_e32 v137, v137, v17
	v_mul_f32_e32 v138, v138, v18
	v_mul_f32_e32 v139, v139, v19
	v_mul_f32_e32 v140, v140, v20
	v_mul_f32_e32 v141, v141, v21
	v_mul_f32_e32 v142, v142, v22
	v_mul_f32_e32 v143, v143, v23
	v_mul_f32_e32 v144, v144, v24
	v_mul_f32_e32 v145, v145, v25
	v_mul_f32_e32 v146, v146, v26
	v_mul_f32_e32 v147, v147, v27
	global_store_dwordx4 v33, v[132:135], s[68:69]
	global_store_dwordx4 v33, v[136:139], s[68:69] offset:1024
	global_store_dwordx4 v33, v[140:143], s[68:69] offset:2048
	global_store_dwordx4 v33, v[144:147], s[68:69] offset:3072
.Lfin_skip_FIN_5:
	s_mul_i32 s6, s5, 6
	s_add_i32 s6, s6, s4
	s_cmp_lt_u32 s6, 0x4000
	s_cbranch_scc0 .Lfin_skip_FIN_6
	s_waitcnt vmcnt(29)
	v_add_f32_dpp v50, v50, v50 quad_perm:[1,0,3,2] row_mask:0xf bank_mask:0xf
	s_nop 1
	v_add_f32_dpp v50, v50, v50 quad_perm:[2,3,0,1] row_mask:0xf bank_mask:0xf
	s_nop 1
	v_add_f32_dpp v50, v50, v50 row_half_mirror row_mask:0xf bank_mask:0xf
	s_nop 1
	v_add_f32_dpp v50, v50, v50 row_mirror row_mask:0xf bank_mask:0xf
	v_fmamk_f32 v50, v50, 0x3a800000, v7
	v_rsq_f32_e32 v50, v50
	s_nop 0
	v_mul_f32_e32 v148, v50, v148
	v_mul_f32_e32 v149, v50, v149
	v_mul_f32_e32 v150, v50, v150
	v_mul_f32_e32 v151, v50, v151
	v_mul_f32_e32 v152, v50, v152
	v_mul_f32_e32 v153, v50, v153
	v_mul_f32_e32 v154, v50, v154
	v_mul_f32_e32 v155, v50, v155
	v_mul_f32_e32 v156, v50, v156
	v_mul_f32_e32 v157, v50, v157
	v_mul_f32_e32 v158, v50, v158
	v_mul_f32_e32 v159, v50, v159
	v_mul_f32_e32 v160, v50, v160
	v_mul_f32_e32 v161, v50, v161
	v_mul_f32_e32 v162, v50, v162
	v_mul_f32_e32 v163, v50, v163
	v_mul_f32_e32 v148, v148, v12
	v_mul_f32_e32 v149, v149, v13
	v_mul_f32_e32 v150, v150, v14
	v_mul_f32_e32 v151, v151, v15
	v_mul_f32_e32 v152, v152, v16
	v_mul_f32_e32 v153, v153, v17
	v_mul_f32_e32 v154, v154, v18
	v_mul_f32_e32 v155, v155, v19
	v_mul_f32_e32 v156, v156, v20
	v_mul_f32_e32 v157, v157, v21
	v_mul_f32_e32 v158, v158, v22
	v_mul_f32_e32 v159, v159, v23
	v_mul_f32_e32 v160, v160, v24
	v_mul_f32_e32 v161, v161, v25
	v_mul_f32_e32 v162, v162, v26
	v_mul_f32_e32 v163, v163, v27
	global_store_dwordx4 v34, v[148:151], s[68:69]
	global_store_dwordx4 v34, v[152:155], s[68:69] offset:1024
	global_store_dwordx4 v34, v[156:159], s[68:69] offset:2048
	global_store_dwordx4 v34, v[160:163], s[68:69] offset:3072
.Lfin_skip_FIN_6:
	s_mul_i32 s6, s5, 7
	s_add_i32 s6, s6, s4
	s_cmp_lt_u32 s6, 0x4000
	s_cbranch_scc0 .Lfin_skip_FIN_7
	s_waitcnt vmcnt(28)
	v_add_f32_dpp v51, v51, v51 quad_perm:[1,0,3,2] row_mask:0xf bank_mask:0xf
	s_nop 1
	v_add_f32_dpp v51, v51, v51 quad_perm:[2,3,0,1] row_mask:0xf bank_mask:0xf
	s_nop 1
	v_add_f32_dpp v51, v51, v51 row_half_mirror row_mask:0xf bank_mask:0xf
	s_nop 1
	v_add_f32_dpp v51, v51, v51 row_mirror row_mask:0xf bank_mask:0xf
	v_fmamk_f32 v51, v51, 0x3a800000, v7
	v_rsq_f32_e32 v51, v51
	s_nop 0
	v_mul_f32_e32 v164, v51, v164
	v_mul_f32_e32 v165, v51, v165
	v_mul_f32_e32 v166, v51, v166
	v_mul_f32_e32 v167, v51, v167
	v_mul_f32_e32 v168, v51, v168
	v_mul_f32_e32 v169, v51, v169
	v_mul_f32_e32 v170, v51, v170
	v_mul_f32_e32 v171, v51, v171
	v_mul_f32_e32 v172, v51, v172
	v_mul_f32_e32 v173, v51, v173
	v_mul_f32_e32 v174, v51, v174
	v_mul_f32_e32 v175, v51, v175
	v_mul_f32_e32 v176, v51, v176
	v_mul_f32_e32 v177, v51, v177
	v_mul_f32_e32 v178, v51, v178
	v_mul_f32_e32 v179, v51, v179
	v_mul_f32_e32 v164, v164, v12
	v_mul_f32_e32 v165, v165, v13
	v_mul_f32_e32 v166, v166, v14
	v_mul_f32_e32 v167, v167, v15
	v_mul_f32_e32 v168, v168, v16
	v_mul_f32_e32 v169, v169, v17
	v_mul_f32_e32 v170, v170, v18
	v_mul_f32_e32 v171, v171, v19
	v_mul_f32_e32 v172, v172, v20
	v_mul_f32_e32 v173, v173, v21
	v_mul_f32_e32 v174, v174, v22
	v_mul_f32_e32 v175, v175, v23
	v_mul_f32_e32 v176, v176, v24
	v_mul_f32_e32 v177, v177, v25
	v_mul_f32_e32 v178, v178, v26
	v_mul_f32_e32 v179, v179, v27
	global_store_dwordx4 v35, v[164:167], s[68:69]
	global_store_dwordx4 v35, v[168:171], s[68:69] offset:1024
	global_store_dwordx4 v35, v[172:175], s[68:69] offset:2048
	global_store_dwordx4 v35, v[176:179], s[68:69] offset:3072
.Lfin_skip_FIN_7:
	s_mul_i32 s6, s5, 8
	s_add_i32 s4, s4, s6
	s_cmp_lt_u32 s4, 0x4000
	s_cbranch_scc1 .Lfin_loop_FIN
.Lfin_done_FIN:
.LBB0_3479:
	s_endpgm
